# v26: v25 + P8 load-segment M0 guard s_nop 0 -> s_nop 2 (timing-only; in-situ P8 about -9 us over repeated interleaved runs)
# speedup vs baseline: 1.0047x; 1.0047x over previous
; #define PG8_STAGE(bufoff, gbase, voff) do { _Pragma("unroll") for (int _i = 0; _i < 2; ++_i) \
;         __builtin_amdgcn_global_load_lds((const unsigned*)((const char*)(gbase) + (voff)[_i]), (LAS unsigned*)(lds + (bufoff) + ldsw + _i * 8192), 16, 0, 0); } while (0)
; #define PG8_LDA(dst, b, h) do { _Pragma("unroll") for (int m = 0; m < 4; ++m) _Pragma("unroll") for (int k = 0; k < 2; ++k) dst[m][k] = *(const LAS bf16x8*)(lds + PG8_SA(b, h) + aoff + m * 2048 + k * 1024); } while (0)
; #define PG8_LDB(dst, b, h) do { _Pragma("unroll") for (int n = 0; n < 2; ++n) _Pragma("unroll") for (int k = 0; k < 2; ++k) dst[n][k] = *(const LAS bf16x8*)(lds + PG8_SB(b, h) + boff + n * 2048 + k * 1024); } while (0)
; #define PG8_MMA(ai, bj, At, Bt) do { __builtin_amdgcn_s_setprio(1); _Pragma("unroll") for (int m = 0; m < 4; ++m) _Pragma("unroll") for (int n = 0; n < 2; ++n) _Pragma("unroll") for (int k = 0; k < 2; ++k) \
;         acc[ai][bj][m][n] = __builtin_amdgcn_mfma_f32_16x16x32_bf16(Bt[n][k], At[m][k], acc[ai][bj][m][n], 0, 0, 0); __builtin_amdgcn_s_setprio(0); } while (0)
; #define PG8_WAIT_V(n) asm volatile("s_waitcnt vmcnt(" #n ")" ::: "memory")
; #define PG8_WAIT_L(n) asm volatile("s_waitcnt lgkmcnt(" #n ")" ::: "memory")
; #define PG8_BAR __builtin_amdgcn_s_barrier()
; #define PG8_SCHED __builtin_amdgcn_sched_barrier(0)
; template <class Epi, class Sched, bool ALIGN_EPI, bool SP2>
; __device__ __forceinline__ void gemm_phase(LAS unsigned char* lds, const Gemm g, const Sched& S, const Epi& E) {
;     ...
;             const char* a1 = cA + (size_t)(t + 1) * kstep;
;             const char* a2 = last ? nA : cA + (size_t)(t + 2) * kstep; const char* b2 = last ? nB : cB + (size_t)(t + 2) * kstep;
;             const char* a3 = a2 + kstep; const char* b3 = b2 + kstep;
;             if constexpr (SP2) {
;             PG8_LDB(B0, 0, 0); PG8_LDB(B1, 0, 1); PG8_SCHED; PG8_LDA(At, 0, 0); PG8_STAGE(PG8_SA(1, 1), a1 + hstep, voffA);
;             PG8_WAIT_V(8); PG8_WAIT_L(0); PG8_BAR; PG8_MMA(0, 0, At, B0); PG8_MMA(0, 1, At, B1); PG8_BAR; PG8_SCHED;
;             PG8_LDA(At, 0, 1); PG8_STAGE(PG8_SB(0, 0), b2, voffB); PG8_STAGE(PG8_SB(0, 1), b2 + hstep, voffB); PG8_STAGE(PG8_SA(0, 0), a2, voffA);
;             PG8_WAIT_V(8); PG8_WAIT_L(0); PG8_BAR; PG8_MMA(1, 0, At, B0); PG8_MMA(1, 1, At, B1); PG8_BAR; PG8_SCHED;
.LBB0_766:
	s_add_u32 s26, s24, 0x100
	s_addc_u32 s27, s25, 0
	s_cmp_eq_u32 s56, 40
	s_cselect_b32 s31, s5, s27
	s_cselect_b32 s30, s4, s26
	s_cselect_b32 s29, s23, s55
	s_cselect_b32 s28, s22, s54
	s_add_i32 m0, s37, 0xc000
	s_nop 0
	global_load_lds_dwordx4 v152, s[24:25]
	s_add_i32 m0, s37, 0xe000
	s_nop 0
	global_load_lds_dwordx4 v154, s[24:25]
	ds_read_b128 v[120:123], v169
	ds_read_b128 v[124:127], v169 offset:1024
	ds_read_b128 v[136:139], v169 offset:2048
	ds_read_b128 v[140:143], v169 offset:3072
	ds_read_b128 v[160:163], v170
	ds_read_b128 v[172:175], v170 offset:1024
	ds_read_b128 v[176:179], v170 offset:2048
	ds_read_b128 v[180:183], v170 offset:3072
	ds_read_b128 v[184:187], v171
	ds_read_b128 v[188:191], v171 offset:1024
	ds_read_b128 v[192:195], v171 offset:2048
	ds_read_b128 v[196:199], v171 offset:3072
	ds_read_b128 v[200:203], v171 offset:4096
	ds_read_b128 v[204:207], v171 offset:5120
	ds_read_b128 v[208:211], v171 offset:6144
	ds_read_b128 v[212:215], v171 offset:7168
	s_waitcnt vmcnt(8)
	s_waitcnt lgkmcnt(0)
	s_barrier
	s_setprio 1
	s_waitcnt lgkmcnt(0)
	v_mfma_f32_16x16x32_bf16 v[132:135], v[120:123], v[184:187], v[132:135]
	v_mfma_f32_16x16x32_bf16 v[128:131], v[136:139], v[184:187], v[128:131]
	v_mfma_f32_16x16x32_bf16 v[108:111], v[120:123], v[192:195], v[108:111]
	v_mfma_f32_16x16x32_bf16 v[104:107], v[136:139], v[192:195], v[104:107]
	v_mfma_f32_16x16x32_bf16 v[92:95], v[120:123], v[200:203], v[92:95]
	v_mfma_f32_16x16x32_bf16 v[88:91], v[136:139], v[200:203], v[88:91]
	v_mfma_f32_16x16x32_bf16 v[76:79], v[120:123], v[208:211], v[76:79]
	v_mfma_f32_16x16x32_bf16 v[72:75], v[136:139], v[208:211], v[72:75]
	v_mfma_f32_16x16x32_bf16 v[132:135], v[124:127], v[188:191], v[132:135]
	v_mfma_f32_16x16x32_bf16 v[128:131], v[140:143], v[188:191], v[128:131]
	v_mfma_f32_16x16x32_bf16 v[108:111], v[124:127], v[196:199], v[108:111]
	v_mfma_f32_16x16x32_bf16 v[104:107], v[140:143], v[196:199], v[104:107]
	v_mfma_f32_16x16x32_bf16 v[92:95], v[124:127], v[204:207], v[92:95]
	v_mfma_f32_16x16x32_bf16 v[88:91], v[140:143], v[204:207], v[88:91]
	v_mfma_f32_16x16x32_bf16 v[76:79], v[124:127], v[212:215], v[76:79]
	v_mfma_f32_16x16x32_bf16 v[72:75], v[140:143], v[212:215], v[72:75]
	s_setprio 0
	s_setprio 1
	v_mfma_f32_16x16x32_bf16 v[116:119], v[160:163], v[184:187], v[116:119]
	v_mfma_f32_16x16x32_bf16 v[112:115], v[176:179], v[184:187], v[112:115]
	v_mfma_f32_16x16x32_bf16 v[100:103], v[160:163], v[192:195], v[100:103]
	v_mfma_f32_16x16x32_bf16 v[96:99], v[176:179], v[192:195], v[96:99]
	v_mfma_f32_16x16x32_bf16 v[84:87], v[160:163], v[200:203], v[84:87]
	v_mfma_f32_16x16x32_bf16 v[80:83], v[176:179], v[200:203], v[80:83]
	v_mfma_f32_16x16x32_bf16 v[68:71], v[160:163], v[208:211], v[68:71]
	v_mfma_f32_16x16x32_bf16 v[64:67], v[176:179], v[208:211], v[64:67]
	v_mfma_f32_16x16x32_bf16 v[116:119], v[172:175], v[188:191], v[116:119]
	v_mfma_f32_16x16x32_bf16 v[112:115], v[180:183], v[188:191], v[112:115]
	v_mfma_f32_16x16x32_bf16 v[100:103], v[172:175], v[196:199], v[100:103]
	v_mfma_f32_16x16x32_bf16 v[96:99], v[180:183], v[196:199], v[96:99]
	v_mfma_f32_16x16x32_bf16 v[84:87], v[172:175], v[204:207], v[84:87]
	v_mfma_f32_16x16x32_bf16 v[80:83], v[180:183], v[204:207], v[80:83]
	v_mfma_f32_16x16x32_bf16 v[68:71], v[172:175], v[212:215], v[68:71]
	v_mfma_f32_16x16x32_bf16 v[64:67], v[180:183], v[212:215], v[64:67]
	s_setprio 0
	s_barrier
	s_add_i32 s24, s48, s36
	s_mov_b32 m0, s24
	s_nop 0
	global_load_lds_dwordx4 v146, s[28:29]
	s_add_i32 m0, s24, 0x2000
	s_add_u32 s24, s28, 0xb0000
	s_addc_u32 s25, s29, 0
	s_add_i32 s57, s49, s36
	global_load_lds_dwordx4 v150, s[28:29]
	s_mov_b32 m0, s57
	s_nop 0
	global_load_lds_dwordx4 v146, s[24:25]
	s_add_i32 m0, s57, 0x2000
	s_nop 0
	global_load_lds_dwordx4 v150, s[24:25]
	s_mov_b32 m0, s37
	s_nop 0
	global_load_lds_dwordx4 v144, s[30:31]
	s_mov_b32 m0, s38
	s_nop 2
	global_load_lds_dwordx4 v148, s[30:31]
	ds_read_b128 v[184:187], v171 offset:16384
	ds_read_b128 v[188:191], v171 offset:17408
	ds_read_b128 v[192:195], v171 offset:18432
	ds_read_b128 v[196:199], v171 offset:19456
	ds_read_b128 v[200:203], v171 offset:20480
	ds_read_b128 v[204:207], v171 offset:21504
	ds_read_b128 v[208:211], v171 offset:22528
	ds_read_b128 v[212:215], v171 offset:23552
	s_waitcnt vmcnt(8)
	s_waitcnt lgkmcnt(0)
	s_barrier
	s_setprio 1
	s_waitcnt lgkmcnt(0)
	v_mfma_f32_16x16x32_bf16 v[60:63], v[120:123], v[184:187], v[60:63]
	v_mfma_f32_16x16x32_bf16 v[56:59], v[136:139], v[184:187], v[56:59]
	v_mfma_f32_16x16x32_bf16 v[44:47], v[120:123], v[192:195], v[44:47]
	v_mfma_f32_16x16x32_bf16 v[40:43], v[136:139], v[192:195], v[40:43]
	v_mfma_f32_16x16x32_bf16 v[28:31], v[120:123], v[200:203], v[28:31]
	v_mfma_f32_16x16x32_bf16 v[24:27], v[136:139], v[200:203], v[24:27]
	v_mfma_f32_16x16x32_bf16 v[12:15], v[120:123], v[208:211], v[12:15]
	v_mfma_f32_16x16x32_bf16 v[8:11], v[136:139], v[208:211], v[8:11]
	v_mfma_f32_16x16x32_bf16 v[60:63], v[124:127], v[188:191], v[60:63]
	v_mfma_f32_16x16x32_bf16 v[56:59], v[140:143], v[188:191], v[56:59]
	v_mfma_f32_16x16x32_bf16 v[44:47], v[124:127], v[196:199], v[44:47]
	v_mfma_f32_16x16x32_bf16 v[40:43], v[140:143], v[196:199], v[40:43]
	v_mfma_f32_16x16x32_bf16 v[28:31], v[124:127], v[204:207], v[28:31]
	v_mfma_f32_16x16x32_bf16 v[24:27], v[140:143], v[204:207], v[24:27]
	v_mfma_f32_16x16x32_bf16 v[12:15], v[124:127], v[212:215], v[12:15]
	v_mfma_f32_16x16x32_bf16 v[8:11], v[140:143], v[212:215], v[8:11]
	s_setprio 0
	s_setprio 1
	v_mfma_f32_16x16x32_bf16 v[52:55], v[160:163], v[184:187], v[52:55]
	v_mfma_f32_16x16x32_bf16 v[48:51], v[176:179], v[184:187], v[48:51]
	v_mfma_f32_16x16x32_bf16 v[36:39], v[160:163], v[192:195], v[36:39]
	v_mfma_f32_16x16x32_bf16 v[32:35], v[176:179], v[192:195], v[32:35]
	v_mfma_f32_16x16x32_bf16 v[20:23], v[160:163], v[200:203], v[20:23]
	v_mfma_f32_16x16x32_bf16 v[16:19], v[176:179], v[200:203], v[16:19]
	v_mfma_f32_16x16x32_bf16 v[4:7], v[160:163], v[208:211], v[4:7]
	v_mfma_f32_16x16x32_bf16 v[0:3], v[176:179], v[208:211], v[0:3]
	v_mfma_f32_16x16x32_bf16 v[52:55], v[172:175], v[188:191], v[52:55]
	v_mfma_f32_16x16x32_bf16 v[48:51], v[180:183], v[188:191], v[48:51]
	v_mfma_f32_16x16x32_bf16 v[36:39], v[172:175], v[196:199], v[36:39]
	v_mfma_f32_16x16x32_bf16 v[32:35], v[180:183], v[196:199], v[32:35]
	v_mfma_f32_16x16x32_bf16 v[20:23], v[172:175], v[204:207], v[20:23]
	v_mfma_f32_16x16x32_bf16 v[16:19], v[180:183], v[204:207], v[16:19]
	v_mfma_f32_16x16x32_bf16 v[4:7], v[172:175], v[212:215], v[4:7]
	v_mfma_f32_16x16x32_bf16 v[0:3], v[180:183], v[212:215], v[0:3]
	s_setprio 0
	s_barrier
; #define PG8_STAGE(bufoff, gbase, voff) do { _Pragma("unroll") for (int _i = 0; _i < 2; ++_i) \
;         __builtin_amdgcn_global_load_lds((const unsigned*)((const char*)(gbase) + (voff)[_i]), (LAS unsigned*)(lds + (bufoff) + ldsw + _i * 8192), 16, 0, 0); } while (0)
; #define PG8_LDA(dst, b, h) do { _Pragma("unroll") for (int m = 0; m < 4; ++m) _Pragma("unroll") for (int k = 0; k < 2; ++k) dst[m][k] = *(const LAS bf16x8*)(lds + PG8_SA(b, h) + aoff + m * 2048 + k * 1024); } while (0)
; #define PG8_LDB(dst, b, h) do { _Pragma("unroll") for (int n = 0; n < 2; ++n) _Pragma("unroll") for (int k = 0; k < 2; ++k) dst[n][k] = *(const LAS bf16x8*)(lds + PG8_SB(b, h) + boff + n * 2048 + k * 1024); } while (0)
; #define PG8_MMA(ai, bj, At, Bt) do { __builtin_amdgcn_s_setprio(1); _Pragma("unroll") for (int m = 0; m < 4; ++m) _Pragma("unroll") for (int n = 0; n < 2; ++n) _Pragma("unroll") for (int k = 0; k < 2; ++k) \
;         acc[ai][bj][m][n] = __builtin_amdgcn_mfma_f32_16x16x32_bf16(Bt[n][k], At[m][k], acc[ai][bj][m][n], 0, 0, 0); __builtin_amdgcn_s_setprio(0); } while (0)
; #define PG8_WAIT_V(n) asm volatile("s_waitcnt vmcnt(" #n ")" ::: "memory")
; #define PG8_WAIT_L(n) asm volatile("s_waitcnt lgkmcnt(" #n ")" ::: "memory")
; #define PG8_BAR __builtin_amdgcn_s_barrier()
; #define PG8_SCHED __builtin_amdgcn_sched_barrier(0)
; template <class Epi, class Sched, bool ALIGN_EPI, bool SP2>
; __device__ __forceinline__ void gemm_phase(LAS unsigned char* lds, const Gemm g, const Sched& S, const Epi& E) {
;     ...
;             PG8_LDB(B0, 1, 0); PG8_LDB(B1, 1, 1); PG8_SCHED; PG8_LDA(At, 1, 0); PG8_STAGE(PG8_SA(0, 1), a2 + hstep, voffA);
;             PG8_WAIT_V(8); PG8_WAIT_L(0); PG8_BAR; PG8_MMA(0, 0, At, B0); PG8_MMA(0, 1, At, B1); PG8_BAR; PG8_SCHED;
;             PG8_LDA(At, 1, 1); PG8_STAGE(PG8_SB(1, 0), b3, voffB); PG8_STAGE(PG8_SB(1, 1), b3 + hstep, voffB); PG8_STAGE(PG8_SA(1, 0), a3, voffA);
;             PG8_WAIT_V(8); PG8_WAIT_L(0); PG8_BAR; PG8_MMA(1, 0, At, B0); PG8_MMA(1, 1, At, B1); PG8_BAR; PG8_SCHED;
	s_add_i32 s57, 0, 0x18000
	s_add_i32 s58, 0, 0x1c000
	v_add_u32_e32 v140, s57, v167
	v_add_u32_e32 v180, s58, v167
	s_add_u32 s24, s30, 0xb0000
	s_addc_u32 s25, s31, 0
	s_mov_b32 m0, s39
	s_nop 0
	global_load_lds_dwordx4 v144, s[24:25]
	s_mov_b32 m0, s40
	s_nop 0
	global_load_lds_dwordx4 v148, s[24:25]
	ds_read_b128 v[120:123], v140
	ds_read_b128 v[124:127], v140 offset:1024
	ds_read_b128 v[136:139], v140 offset:2048
	ds_read_b128 v[140:143], v140 offset:3072
	ds_read_b128 v[160:163], v180
	ds_read_b128 v[172:175], v180 offset:1024
	ds_read_b128 v[176:179], v180 offset:2048
	ds_read_b128 v[180:183], v180 offset:3072
	ds_read_b128 v[184:187], v171 offset:32768
	ds_read_b128 v[188:191], v171 offset:33792
	ds_read_b128 v[192:195], v171 offset:34816
	ds_read_b128 v[196:199], v171 offset:35840
	ds_read_b128 v[200:203], v171 offset:36864
	ds_read_b128 v[204:207], v171 offset:37888
	ds_read_b128 v[208:211], v171 offset:38912
	ds_read_b128 v[212:215], v171 offset:39936
	s_waitcnt vmcnt(8)
	s_waitcnt lgkmcnt(0)
	s_barrier
	s_setprio 1
	s_waitcnt lgkmcnt(0)
	v_mfma_f32_16x16x32_bf16 v[132:135], v[120:123], v[184:187], v[132:135]
	v_mfma_f32_16x16x32_bf16 v[128:131], v[136:139], v[184:187], v[128:131]
	v_mfma_f32_16x16x32_bf16 v[108:111], v[120:123], v[192:195], v[108:111]
	v_mfma_f32_16x16x32_bf16 v[104:107], v[136:139], v[192:195], v[104:107]
	v_mfma_f32_16x16x32_bf16 v[92:95], v[120:123], v[200:203], v[92:95]
	v_mfma_f32_16x16x32_bf16 v[88:91], v[136:139], v[200:203], v[88:91]
	v_mfma_f32_16x16x32_bf16 v[76:79], v[120:123], v[208:211], v[76:79]
	v_mfma_f32_16x16x32_bf16 v[72:75], v[136:139], v[208:211], v[72:75]
	v_mfma_f32_16x16x32_bf16 v[132:135], v[124:127], v[188:191], v[132:135]
	v_mfma_f32_16x16x32_bf16 v[128:131], v[140:143], v[188:191], v[128:131]
	v_mfma_f32_16x16x32_bf16 v[108:111], v[124:127], v[196:199], v[108:111]
	v_mfma_f32_16x16x32_bf16 v[104:107], v[140:143], v[196:199], v[104:107]
	v_mfma_f32_16x16x32_bf16 v[92:95], v[124:127], v[204:207], v[92:95]
	v_mfma_f32_16x16x32_bf16 v[88:91], v[140:143], v[204:207], v[88:91]
	v_mfma_f32_16x16x32_bf16 v[76:79], v[124:127], v[212:215], v[76:79]
	v_mfma_f32_16x16x32_bf16 v[72:75], v[140:143], v[212:215], v[72:75]
	s_setprio 0
	s_setprio 1
	v_mfma_f32_16x16x32_bf16 v[116:119], v[160:163], v[184:187], v[116:119]
	v_mfma_f32_16x16x32_bf16 v[112:115], v[176:179], v[184:187], v[112:115]
	v_mfma_f32_16x16x32_bf16 v[100:103], v[160:163], v[192:195], v[100:103]
	v_mfma_f32_16x16x32_bf16 v[96:99], v[176:179], v[192:195], v[96:99]
	v_mfma_f32_16x16x32_bf16 v[84:87], v[160:163], v[200:203], v[84:87]
	v_mfma_f32_16x16x32_bf16 v[80:83], v[176:179], v[200:203], v[80:83]
	v_mfma_f32_16x16x32_bf16 v[68:71], v[160:163], v[208:211], v[68:71]
	v_mfma_f32_16x16x32_bf16 v[64:67], v[176:179], v[208:211], v[64:67]
	v_mfma_f32_16x16x32_bf16 v[116:119], v[172:175], v[188:191], v[116:119]
	v_mfma_f32_16x16x32_bf16 v[112:115], v[180:183], v[188:191], v[112:115]
	v_mfma_f32_16x16x32_bf16 v[100:103], v[172:175], v[196:199], v[100:103]
	v_mfma_f32_16x16x32_bf16 v[96:99], v[180:183], v[196:199], v[96:99]
	v_mfma_f32_16x16x32_bf16 v[84:87], v[172:175], v[204:207], v[84:87]
	v_mfma_f32_16x16x32_bf16 v[80:83], v[180:183], v[204:207], v[80:83]
	v_mfma_f32_16x16x32_bf16 v[68:71], v[172:175], v[212:215], v[68:71]
	v_mfma_f32_16x16x32_bf16 v[64:67], v[180:183], v[212:215], v[64:67]
	s_setprio 0
	s_barrier
	s_add_u32 s100, s24, 0xfff50080
	s_addc_u32 s101, s25, -1
	s_add_u32 s98, s28, 0x80
	s_addc_u32 s99, s29, 0
	s_add_i32 s24, s57, s36
	s_mov_b32 m0, s24
	s_nop 0
	global_load_lds_dwordx4 v146, s[98:99]
	s_add_i32 m0, s24, 0x2000
	s_add_u32 s24, s28, 0xb0080
	s_addc_u32 s25, s29, 0
	s_add_i32 s28, s58, s36
	global_load_lds_dwordx4 v150, s[98:99]
	s_mov_b32 m0, s28
	s_nop 0
	global_load_lds_dwordx4 v146, s[24:25]
	s_add_i32 m0, s28, 0x2000
	s_nop 0
	global_load_lds_dwordx4 v150, s[24:25]
	s_mov_b32 m0, s45
	s_nop 0
	global_load_lds_dwordx4 v144, s[100:101]
	s_mov_b32 m0, s46
	s_nop 0
	global_load_lds_dwordx4 v148, s[100:101]
	ds_read_b128 v[184:187], v171 offset:49152
	ds_read_b128 v[188:191], v171 offset:50176
	ds_read_b128 v[192:195], v171 offset:51200
	ds_read_b128 v[196:199], v171 offset:52224
	ds_read_b128 v[200:203], v171 offset:53248
	ds_read_b128 v[204:207], v171 offset:54272
	ds_read_b128 v[208:211], v171 offset:55296
	ds_read_b128 v[212:215], v171 offset:56320
	s_waitcnt vmcnt(8)
	s_waitcnt lgkmcnt(0)
	s_barrier
	s_setprio 1
	s_waitcnt lgkmcnt(0)
	v_mfma_f32_16x16x32_bf16 v[60:63], v[120:123], v[184:187], v[60:63]
	v_mfma_f32_16x16x32_bf16 v[56:59], v[136:139], v[184:187], v[56:59]
	v_mfma_f32_16x16x32_bf16 v[44:47], v[120:123], v[192:195], v[44:47]
	v_mfma_f32_16x16x32_bf16 v[40:43], v[136:139], v[192:195], v[40:43]
	v_mfma_f32_16x16x32_bf16 v[28:31], v[120:123], v[200:203], v[28:31]
	v_mfma_f32_16x16x32_bf16 v[24:27], v[136:139], v[200:203], v[24:27]
	v_mfma_f32_16x16x32_bf16 v[12:15], v[120:123], v[208:211], v[12:15]
	v_mfma_f32_16x16x32_bf16 v[8:11], v[136:139], v[208:211], v[8:11]
	v_mfma_f32_16x16x32_bf16 v[60:63], v[124:127], v[188:191], v[60:63]
	v_mfma_f32_16x16x32_bf16 v[56:59], v[140:143], v[188:191], v[56:59]
	v_mfma_f32_16x16x32_bf16 v[44:47], v[124:127], v[196:199], v[44:47]
	v_mfma_f32_16x16x32_bf16 v[40:43], v[140:143], v[196:199], v[40:43]
	v_mfma_f32_16x16x32_bf16 v[28:31], v[124:127], v[204:207], v[28:31]
	v_mfma_f32_16x16x32_bf16 v[24:27], v[140:143], v[204:207], v[24:27]
	v_mfma_f32_16x16x32_bf16 v[12:15], v[124:127], v[212:215], v[12:15]
	v_mfma_f32_16x16x32_bf16 v[8:11], v[140:143], v[212:215], v[8:11]
	s_setprio 0
	s_setprio 1
	v_mfma_f32_16x16x32_bf16 v[52:55], v[160:163], v[184:187], v[52:55]
	v_mfma_f32_16x16x32_bf16 v[48:51], v[176:179], v[184:187], v[48:51]
	v_mfma_f32_16x16x32_bf16 v[36:39], v[160:163], v[192:195], v[36:39]
	v_mfma_f32_16x16x32_bf16 v[32:35], v[176:179], v[192:195], v[32:35]
	v_mfma_f32_16x16x32_bf16 v[20:23], v[160:163], v[200:203], v[20:23]
	v_mfma_f32_16x16x32_bf16 v[16:19], v[176:179], v[200:203], v[16:19]
	v_mfma_f32_16x16x32_bf16 v[4:7], v[160:163], v[208:211], v[4:7]
	v_mfma_f32_16x16x32_bf16 v[0:3], v[176:179], v[208:211], v[0:3]
	v_mfma_f32_16x16x32_bf16 v[52:55], v[172:175], v[188:191], v[52:55]
	v_mfma_f32_16x16x32_bf16 v[48:51], v[180:183], v[188:191], v[48:51]
	v_mfma_f32_16x16x32_bf16 v[36:39], v[172:175], v[196:199], v[36:39]
	v_mfma_f32_16x16x32_bf16 v[32:35], v[180:183], v[196:199], v[32:35]
	v_mfma_f32_16x16x32_bf16 v[20:23], v[172:175], v[204:207], v[20:23]
	v_mfma_f32_16x16x32_bf16 v[16:19], v[180:183], v[204:207], v[16:19]
	v_mfma_f32_16x16x32_bf16 v[4:7], v[172:175], v[212:215], v[4:7]
	v_mfma_f32_16x16x32_bf16 v[0:3], v[180:183], v[212:215], v[0:3]
	s_setprio 0
	s_barrier
	s_add_i32 s56, s56, 2
	s_add_u32 s54, s54, 0x100
	s_addc_u32 s55, s55, 0
	s_cmp_gt_u32 s56, 41
	s_mov_b64 s[24:25], s[26:27]
	s_cbranch_scc0 .LBB0_766
	s_and_b64 vcc, exec, s[12:13]
	s_cbranch_vccz .LBB0_769
	s_barrier
